# v19 + RG-LRU: the loop-top workgroup barrier only before the first task (redundant later: three barriers separate the staging buffers' last reads from their next writes)
# baseline (speedup 1.0000x reference)
.LBB0_307:
	s_and_b32 s41, s40, 7
	s_cmp_eq_u32 s41, s2
	s_cbranch_scc1 .LBB0_309
	s_lshl_b32 s0, s41, 6
	v_or_b32_e32 v18, s0, v121
	s_mov_b64 s[42:43], s[52:53]
	v_readlane_b32 s52, v254, 60
	v_lshlrev_b32_e32 v38, 2, v18
	v_mov_b32_e32 v39, v196
	v_readlane_b32 s64, v255, 8
	v_readlane_b32 s65, v255, 9
	v_readlane_b32 s53, v254, 61
	v_readlane_b32 s54, v254, 62
	v_readlane_b32 s55, v254, 63
	v_readlane_b32 s56, v255, 0
	v_readlane_b32 s57, v255, 1
	v_readlane_b32 s58, v255, 2
	v_readlane_b32 s59, v255, 3
	v_readlane_b32 s60, v255, 4
	v_readlane_b32 s61, v255, 5
	v_readlane_b32 s62, v255, 6
	v_readlane_b32 s63, v255, 7
	v_readlane_b32 s66, v255, 10
	v_readlane_b32 s67, v255, 11
	v_lshl_add_u64 v[50:51], s[64:65], 0, v[38:39]
	s_mov_b64 s[16:17], 0x1000
	s_movk_i32 s1, 0x1000
	s_nop 1
	global_load_dwordx4 v[22:25], v38, s[66:67] offset:16
	global_load_dwordx4 v[18:21], v38, s[64:65] offset:16
	global_load_dwordx4 v[30:33], v38, s[66:67]
	global_load_dwordx4 v[26:29], v38, s[64:65]
	global_load_dwordx4 v[34:37], v38, s[64:65] offset:2064
	s_nop 0
	global_load_dwordx4 v[38:41], v38, s[64:65] offset:2048
	v_lshl_add_u64 v[42:43], v[50:51], 0, s[16:17]
	v_add_co_u32_e32 v52, vcc, s1, v50
	s_mov_b64 s[16:17], 0x1800
	v_or_b32_e32 v58, s0, v120
	v_readlane_b32 s52, v255, 12
	v_readlane_b32 s0, v255, 43
	v_addc_co_u32_e32 v53, vcc, 0, v51, vcc
	v_lshl_add_u64 v[50:51], v[50:51], 0, s[16:17]
	v_lshlrev_b32_e32 v58, 2, v58
	v_readlane_b32 s54, v255, 14
	v_readlane_b32 s55, v255, 15
	v_readlane_b32 s1, v255, 44
	global_load_dwordx4 v[46:49], v[52:53], off
	s_nop 0
	global_load_dwordx4 v[42:45], v[42:43], off offset:16
	s_nop 0
	global_load_dwordx4 v[54:57], v[52:53], off offset:2048
	s_nop 0
	global_load_dwordx4 v[50:53], v[50:51], off offset:16
	v_readlane_b32 s58, v255, 18
	v_readlane_b32 s59, v255, 19
	global_load_dword v153, v58, s[54:55]
	s_nop 3
	global_load_dword v154, v58, s[58:59]
	global_load_dword v155, v58, s[0:1]
	s_lshl_b32 s0, s41, 13
	s_mov_b32 s1, s46
	v_lshl_add_u64 v[74:75], v[96:97], 0, s[0:1]
	global_load_dwordx4 v[70:73], v[74:75], off
	global_load_dwordx4 v[66:69], v[74:75], off offset:64
	global_load_dwordx4 v[62:65], v[74:75], off offset:2048
	global_load_dwordx4 v[58:61], v[74:75], off offset:2112
	v_add_co_u32_e32 v74, vcc, 0x1000, v74
	v_readlane_b32 s60, v255, 20
	s_nop 0
	v_addc_co_u32_e32 v75, vcc, 0, v75, vcc
	global_load_dwordx4 v[86:89], v[74:75], off
	global_load_dwordx4 v[82:85], v[74:75], off offset:64
	global_load_dwordx4 v[78:81], v[74:75], off offset:2048
	s_nop 0
	global_load_dwordx4 v[74:77], v[74:75], off offset:2112
	v_readlane_b32 s61, v255, 21
	v_readlane_b32 s62, v255, 22
	v_readlane_b32 s63, v255, 23
	v_readlane_b32 s53, v255, 13
	v_readlane_b32 s62, v255, 51
	v_readlane_b32 s60, v255, 49
	s_mov_b64 s[52:53], s[42:43]
	v_readlane_b32 s63, v255, 52
	v_readlane_b32 s61, v255, 50
	s_mov_b32 s2, s41
	v_readlane_b32 s56, v255, 16
	v_readlane_b32 s57, v255, 17
	v_readlane_b32 s64, v255, 24
	v_readlane_b32 s65, v255, 25
	v_readlane_b32 s66, v255, 26
	v_readlane_b32 s67, v255, 27
	s_waitcnt vmcnt(0)
	s_barrier
.LBB0_309:
	v_lshlrev_b32_e32 v98, 16, v6
	v_and_b32_e32 v99, 0xffff0000, v6
	v_pk_fma_f32 v[98:99], v[26:27], v[98:99], v[30:31]
	v_lshlrev_b32_e32 v100, 16, v2
	v_and_b32_e32 v101, 0xffff0000, v2
	v_pk_fma_f32 v[98:99], v[38:39], v[100:101], v[98:99]
	v_lshlrev_b32_e32 v100, 16, v10
	v_and_b32_e32 v101, 0xffff0000, v10
	v_pk_fma_f32 v[98:99], v[46:47], v[100:101], v[98:99]
	v_lshlrev_b32_e32 v100, 16, v14
	v_and_b32_e32 v101, 0xffff0000, v14
	v_pk_fma_f32 v[98:99], v[54:55], v[100:101], v[98:99]
	v_lshlrev_b32_e32 v100, 16, v7
	v_and_b32_e32 v101, 0xffff0000, v7
	v_pk_fma_f32 v[100:101], v[28:29], v[100:101], v[32:33]
	v_lshlrev_b32_e32 v102, 16, v3
	v_and_b32_e32 v103, 0xffff0000, v3
	v_pk_fma_f32 v[100:101], v[40:41], v[102:103], v[100:101]
	v_lshlrev_b32_e32 v102, 16, v11
	v_and_b32_e32 v103, 0xffff0000, v11
	v_pk_fma_f32 v[100:101], v[48:49], v[102:103], v[100:101]
	v_lshlrev_b32_e32 v102, 16, v15
	v_and_b32_e32 v103, 0xffff0000, v15
	v_pk_fma_f32 v[100:101], v[56:57], v[102:103], v[100:101]
	v_lshlrev_b32_e32 v102, 16, v8
	v_and_b32_e32 v103, 0xffff0000, v8
	s_load_dword s15, s[78:79], 0x0
	v_pk_fma_f32 v[102:103], v[18:19], v[102:103], v[22:23]
	v_lshlrev_b32_e32 v104, 16, v4
	v_and_b32_e32 v105, 0xffff0000, v4
	v_pk_fma_f32 v[102:103], v[34:35], v[104:105], v[102:103]
	v_lshlrev_b32_e32 v104, 16, v12
	v_and_b32_e32 v105, 0xffff0000, v12
	v_pk_fma_f32 v[102:103], v[42:43], v[104:105], v[102:103]
	v_lshlrev_b32_e32 v104, 16, v16
	v_and_b32_e32 v105, 0xffff0000, v16
	v_pk_fma_f32 v[102:103], v[50:51], v[104:105], v[102:103]
	v_lshlrev_b32_e32 v104, 16, v9
	v_and_b32_e32 v105, 0xffff0000, v9
	v_pk_fma_f32 v[104:105], v[20:21], v[104:105], v[24:25]
	v_lshlrev_b32_e32 v106, 16, v5
	v_and_b32_e32 v107, 0xffff0000, v5
	s_waitcnt lgkmcnt(0)
	s_add_i32 s15, s15, s40
	v_pk_fma_f32 v[104:105], v[36:37], v[106:107], v[104:105]
	v_lshlrev_b32_e32 v106, 16, v13
	v_and_b32_e32 v107, 0xffff0000, v13
	s_cmpk_gt_i32 s15, 0x7ff
	v_pk_fma_f32 v[104:105], v[44:45], v[106:107], v[104:105]
	v_lshlrev_b32_e32 v106, 16, v17
	v_and_b32_e32 v107, 0xffff0000, v17
	s_cselect_b64 s[16:17], -1, 0
	v_pk_fma_f32 v[104:105], v[52:53], v[106:107], v[104:105]
	v_cvt_pk_bf16_f32 v106, v98, v99
	v_cvt_pk_bf16_f32 v107, v100, v101
	v_cvt_pk_bf16_f32 v108, v102, v103
	v_add_u32_e32 v110, v122, v90
	v_cvt_pk_bf16_f32 v109, v104, v105
	s_and_b64 vcc, exec, s[16:17]
	ds_write_b128 v110, v[106:109]
	ds_write_b128 v123, v[98:101] offset:9216
	ds_write_b128 v123, v[102:105] offset:9232
	s_cbranch_vccnz .LBB0_319
	s_lshl_b32 s0, s15, 8
	s_and_b32 s42, s15, 0xffffffc0
	s_and_b32 s33, s0, 0x3800
	s_lshl_b32 s0, s15, 7
	v_add_u32_e32 v14, s42, v124
	s_and_b32 s0, s0, 0x380
	s_mov_b32 s1, s46
	v_mov_b32_e32 v2, v196
	v_mov_b32_e32 v3, v196
	v_lshl_add_u64 v[98:99], v[92:93], 0, s[0:1]
	v_cmp_lt_i32_e32 vcc, -1, v14
	v_mov_b64_e32 v[6:7], v[2:3]
	v_mov_b64_e32 v[8:9], v[2:3]
	s_and_saveexec_b64 s[0:1], vcc
	s_cbranch_execz .LBB0_312
	v_add_u32_e32 v4, s33, v14
	s_movk_i32 s43, 0xc00
	v_mad_u64_u32 v[4:5], s[44:45], v4, s43, v[98:99]
	global_load_dwordx4 v[6:9], v[4:5], off
